# K-loop trims combined: setprio flips deleted, duplicate lgkmcnt(0) waits removed, G copy B0 read rebalancing
# baseline (speedup 1.0000x reference)
; #define LDA(dst, b, h) for (int m = 0; m < 4; ++m) for (int k = 0; k < 2; ++k) \
;     dst[m][k] = *reinterpret_cast<const bf16x8*>((char*)SA(b, h) + lds_byte(wr * 64 + m * 16 + fr, k * 32 + fq * 8))
; #define LDB(dst, b, h) for (int n = 0; n < 2; ++n) for (int k = 0; k < 2; ++k) \
;     dst[n][k] = *reinterpret_cast<const bf16x8*>((char*)SB(b, h) + lds_byte(wc * 32 + n * 16 + fr, k * 32 + fq * 8))
; #define MMA(ai, bj, At_, Bt_) do { __builtin_amdgcn_s_setprio(1); \
;     for (int m = 0; m < 4; ++m) for (int n = 0; n < 2; ++n) for (int k = 0; k < 2; ++k) \
;       acc[ai][bj][m][n] = MFMA16(Bt_[n][k], At_[m][k], acc[ai][bj][m][n]); \
;     __builtin_amdgcn_s_setprio(0); } while (0)
; #define WAIT_L(n) asm volatile("s_waitcnt lgkmcnt(" #n ")" ::: "memory")
; #define BAR __builtin_amdgcn_s_barrier()
; #define SCHED __builtin_amdgcn_sched_barrier(0)
; template <int PART  , bool SYNC_FIRST = true>
; __device__ __forceinline__ void kloop_t(const u16* __restrict__ A, int lda, const u16* __restrict__ Bt, int ldb, int K, Acc& acc, const int wv) {
;     ...
;     LDB(B0, 0, 0); SCHED; LDA(At, 0, 0); STAGE(SA(1, 1), A, lda, HALF, t + 1);
;     WAIT_L(8); BAR; WAIT_L(0); MMA(0, 0, At, B0); BAR; SCHED;
;     LDB(B1, 0, 1); STAGE(SB(0, 0), Bt, ldb, 0, t + 2);
;     BAR; WAIT_L(0); MMA(0, 1, At, B1); BAR;
;     LDA(At, 0, 1); STAGE(SA(0, 0), A, lda, 0, t + 2);
;     BAR; WAIT_L(0); MMA(1, 0, At, B0); BAR; SCHED;
.LBB0_1139:
	s_add_u32 s44, s42, s56
	v_mov_b32_e32 v170, v131
	v_mov_b32_e32 v128, v130
	s_addc_u32 s45, s43, 0
	ds_read_b128 v[190:193], v132
	ds_read_b128 v[194:197], v133
	ds_read_b128 v[198:201], v134
	ds_read_b128 v[202:205], v135
	ds_read_b128 v[206:209], v136
	ds_read_b128 v[210:213], v137
	ds_read_b128 v[214:217], v138
	ds_read_b128 v[218:221], v139
	v_mov_b32_e32 v171, v129
	v_lshl_add_u64 v[168:169], s[44:45], 0, v[128:129]
	v_lshl_add_u64 v[172:173], v[168:169], 0, s[24:25]
	v_add_u32_e32 v168, 0xc000, v144
	v_add_u32_e32 v169, 0xe000, v144
	v_readfirstlane_b32 s52, v168
	s_mov_b32 m0, s52
	v_lshl_add_u64 v[170:171], s[44:45], 0, v[170:171]
	v_readfirstlane_b32 s52, v169
	global_load_lds_dwordx4 v[172:173], off
	v_lshl_add_u64 v[170:171], v[170:171], 0, s[24:25]
	s_mov_b32 m0, s52
	s_nop 0
	global_load_lds_dwordx4 v[170:171], off
	s_waitcnt lgkmcnt(8)
	s_barrier
	s_waitcnt lgkmcnt(0)
	v_mfma_f32_16x16x32_bf16 v[124:127], v[174:177], v[190:193], v[124:127]
	v_mfma_f32_16x16x32_bf16 v[120:123], v[182:185], v[190:193], v[120:123]
	v_mfma_f32_16x16x32_bf16 v[116:119], v[174:177], v[198:201], v[116:119]
	v_mfma_f32_16x16x32_bf16 v[112:115], v[182:185], v[198:201], v[112:115]
	v_mfma_f32_16x16x32_bf16 v[108:111], v[174:177], v[206:209], v[108:111]
	v_mfma_f32_16x16x32_bf16 v[104:107], v[182:185], v[206:209], v[104:107]
	v_mfma_f32_16x16x32_bf16 v[100:103], v[174:177], v[214:217], v[100:103]
	v_mfma_f32_16x16x32_bf16 v[96:99], v[182:185], v[214:217], v[96:99]
	v_mfma_f32_16x16x32_bf16 v[124:127], v[178:181], v[194:197], v[124:127]
	v_mfma_f32_16x16x32_bf16 v[120:123], v[186:189], v[194:197], v[120:123]
	v_mfma_f32_16x16x32_bf16 v[116:119], v[178:181], v[202:205], v[116:119]
	v_mfma_f32_16x16x32_bf16 v[112:115], v[186:189], v[202:205], v[112:115]
	v_mfma_f32_16x16x32_bf16 v[108:111], v[178:181], v[210:213], v[108:111]
	v_mfma_f32_16x16x32_bf16 v[104:107], v[186:189], v[210:213], v[104:107]
	v_mfma_f32_16x16x32_bf16 v[100:103], v[178:181], v[218:221], v[100:103]
	v_mfma_f32_16x16x32_bf16 v[96:99], v[186:189], v[218:221], v[96:99]
	s_barrier
	s_add_u32 s52, s42, s55
	v_add_u32_e32 v170, v157, v160
	v_add_u32_e32 v172, v157, v162
	v_mov_b32_e32 v238, v131
	v_mov_b32_e32 v128, v130
	s_addc_u32 s53, s43, 0
	v_add_u32_e32 v171, v157, v161
	ds_read_b128 v[222:225], v170
	ds_read_b128 v[226:229], v171
	v_add_u32_e32 v173, v157, v163
	ds_read_b128 v[230:233], v172
	ds_read_b128 v[234:237], v173
	v_readfirstlane_b32 s87, v142
	v_lshl_add_u64 v[240:241], s[52:53], 0, v[128:129]
	v_mov_b32_e32 v239, v129
	v_lshl_add_u64 v[240:241], v[240:241], 0, s[26:27]
	s_mov_b32 m0, s87
	v_lshl_add_u64 v[238:239], s[52:53], 0, v[238:239]
	v_readfirstlane_b32 s87, v143
	global_load_lds_dwordx4 v[240:241], off
	v_lshl_add_u64 v[238:239], v[238:239], 0, s[26:27]
	s_mov_b32 m0, s87
	s_nop 0
	global_load_lds_dwordx4 v[238:239], off
	s_barrier
	s_waitcnt lgkmcnt(0)
	v_mfma_f32_16x16x32_bf16 v[92:95], v[222:225], v[190:193], v[92:95]
	v_mfma_f32_16x16x32_bf16 v[88:91], v[230:233], v[190:193], v[88:91]
	v_mfma_f32_16x16x32_bf16 v[84:87], v[222:225], v[198:201], v[84:87]
	v_mfma_f32_16x16x32_bf16 v[80:83], v[230:233], v[198:201], v[80:83]
	v_mfma_f32_16x16x32_bf16 v[76:79], v[222:225], v[206:209], v[76:79]
	v_mfma_f32_16x16x32_bf16 v[72:75], v[230:233], v[206:209], v[72:75]
	v_mfma_f32_16x16x32_bf16 v[68:71], v[222:225], v[214:217], v[68:71]
	v_mfma_f32_16x16x32_bf16 v[64:67], v[230:233], v[214:217], v[64:67]
	v_mfma_f32_16x16x32_bf16 v[92:95], v[226:229], v[194:197], v[92:95]
	v_mfma_f32_16x16x32_bf16 v[88:91], v[234:237], v[194:197], v[88:91]
	v_mfma_f32_16x16x32_bf16 v[84:87], v[226:229], v[202:205], v[84:87]
	v_mfma_f32_16x16x32_bf16 v[80:83], v[234:237], v[202:205], v[80:83]
	v_mfma_f32_16x16x32_bf16 v[76:79], v[226:229], v[210:213], v[76:79]
	v_mfma_f32_16x16x32_bf16 v[72:75], v[234:237], v[210:213], v[72:75]
	v_mfma_f32_16x16x32_bf16 v[68:71], v[226:229], v[218:221], v[68:71]
	v_mfma_f32_16x16x32_bf16 v[64:67], v[234:237], v[218:221], v[64:67]
	v_mov_b32_e32 v238, v131
	v_mov_b32_e32 v128, v130
	s_barrier
	ds_read_b128 v[190:193], v132 offset:16384
	ds_read_b128 v[194:197], v133 offset:16384
	ds_read_b128 v[198:201], v134 offset:16384
	ds_read_b128 v[202:205], v135 offset:16384
	ds_read_b128 v[206:209], v136 offset:16384
	ds_read_b128 v[210:213], v137 offset:16384
	ds_read_b128 v[214:217], v138 offset:16384
	ds_read_b128 v[218:221], v139 offset:16384
	v_readfirstlane_b32 s87, v144
	v_lshl_add_u64 v[240:241], s[44:45], 0, v[128:129]
	v_mov_b32_e32 v239, v129
	v_lshl_add_u64 v[240:241], v[240:241], 0, s[28:29]
	s_mov_b32 m0, s87
	v_lshl_add_u64 v[238:239], s[44:45], 0, v[238:239]
	v_readfirstlane_b32 s87, v145
	global_load_lds_dwordx4 v[240:241], off
	v_lshl_add_u64 v[238:239], v[238:239], 0, s[28:29]
	s_mov_b32 m0, s87
	s_nop 0
	global_load_lds_dwordx4 v[238:239], off
	s_waitcnt vmcnt(10)
	s_barrier
	s_waitcnt lgkmcnt(0)
	v_mfma_f32_16x16x32_bf16 v[60:63], v[174:177], v[190:193], v[60:63]
	v_mfma_f32_16x16x32_bf16 v[56:59], v[182:185], v[190:193], v[56:59]
	v_mfma_f32_16x16x32_bf16 v[52:55], v[174:177], v[198:201], v[52:55]
	v_mfma_f32_16x16x32_bf16 v[48:51], v[182:185], v[198:201], v[48:51]
	v_mfma_f32_16x16x32_bf16 v[44:47], v[174:177], v[206:209], v[44:47]
	v_mfma_f32_16x16x32_bf16 v[40:43], v[182:185], v[206:209], v[40:43]
	v_mfma_f32_16x16x32_bf16 v[36:39], v[174:177], v[214:217], v[36:39]
	v_mfma_f32_16x16x32_bf16 v[32:35], v[182:185], v[214:217], v[32:35]
	v_mfma_f32_16x16x32_bf16 v[60:63], v[178:181], v[194:197], v[60:63]
	v_mfma_f32_16x16x32_bf16 v[56:59], v[186:189], v[194:197], v[56:59]
	v_mfma_f32_16x16x32_bf16 v[52:55], v[178:181], v[202:205], v[52:55]
	v_mfma_f32_16x16x32_bf16 v[48:51], v[186:189], v[202:205], v[48:51]
	v_mfma_f32_16x16x32_bf16 v[44:47], v[178:181], v[210:213], v[44:47]
	v_mfma_f32_16x16x32_bf16 v[40:43], v[186:189], v[210:213], v[40:43]
	v_mfma_f32_16x16x32_bf16 v[36:39], v[178:181], v[218:221], v[36:39]
	v_mfma_f32_16x16x32_bf16 v[32:35], v[186:189], v[218:221], v[32:35]
	s_barrier
; #define LDA(dst, b, h) for (int m = 0; m < 4; ++m) for (int k = 0; k < 2; ++k) \
;     dst[m][k] = *reinterpret_cast<const bf16x8*>((char*)SA(b, h) + lds_byte(wr * 64 + m * 16 + fr, k * 32 + fq * 8))
; #define LDB(dst, b, h) for (int n = 0; n < 2; ++n) for (int k = 0; k < 2; ++k) \
;     dst[n][k] = *reinterpret_cast<const bf16x8*>((char*)SB(b, h) + lds_byte(wc * 32 + n * 16 + fr, k * 32 + fq * 8))
; #define MMA(ai, bj, At_, Bt_) do { __builtin_amdgcn_s_setprio(1); \
;     for (int m = 0; m < 4; ++m) for (int n = 0; n < 2; ++n) for (int k = 0; k < 2; ++k) \
;       acc[ai][bj][m][n] = MFMA16(Bt_[n][k], At_[m][k], acc[ai][bj][m][n]); \
;     __builtin_amdgcn_s_setprio(0); } while (0)
; #define WAIT_V(n) asm volatile("s_waitcnt vmcnt(" #n ")" ::: "memory")
; #define WAIT_L(n) asm volatile("s_waitcnt lgkmcnt(" #n ")" ::: "memory")
; #define BAR __builtin_amdgcn_s_barrier()
; #define SCHED __builtin_amdgcn_sched_barrier(0)
; template <int PART  , bool SYNC_FIRST = true>
; __device__ __forceinline__ void kloop_t(const u16* __restrict__ A, int lda, const u16* __restrict__ Bt, int ldb, int K, Acc& acc, const int wv) {
;     ...
;     STAGE(SB(0, 1), Bt, ldb, HALF, t + 2);
;     WAIT_V(6); BAR; MMA(1, 1, At, B1); BAR;
;     LDB(B0, 1, 0); SCHED; LDA(At, 1, 0); STAGE(SA(0, 1), A, lda, HALF, t + 2);
;     WAIT_L(8); BAR; WAIT_L(0); MMA(0, 0, At, B0); BAR; SCHED;
;     LDB(B1, 1, 1); STAGE(SB(1, 0), Bt, ldb, 0, t + 3);
;     BAR; WAIT_L(0); MMA(0, 1, At, B1); BAR;
;     LDA(At, 1, 1); STAGE(SA(1, 0), A, lda, 0, t + 3);
;     BAR; WAIT_L(0); MMA(1, 0, At, B0); BAR; SCHED;
	v_mov_b32_e32 v174, v131
	v_mov_b32_e32 v128, v130
	v_readfirstlane_b32 s87, v146
	v_lshl_add_u64 v[176:177], s[52:53], 0, v[128:129]
	v_mov_b32_e32 v175, v129
	v_lshl_add_u64 v[176:177], v[176:177], 0, s[30:31]
	s_mov_b32 m0, s87
	v_lshl_add_u64 v[174:175], s[52:53], 0, v[174:175]
	v_readfirstlane_b32 s87, v147
	global_load_lds_dwordx4 v[176:177], off
	v_lshl_add_u64 v[174:175], v[174:175], 0, s[30:31]
	s_mov_b32 m0, s87
	s_nop 0
	global_load_lds_dwordx4 v[174:175], off
	v_add_u32_e32 v174, v158, v160
	v_add_u32_e32 v175, v158, v161
	v_add_u32_e32 v176, v158, v162
	v_add_u32_e32 v177, v158, v163
	s_waitcnt vmcnt(6)
	s_barrier
	v_mfma_f32_16x16x32_bf16 v[28:31], v[222:225], v[190:193], v[28:31]
	v_mfma_f32_16x16x32_bf16 v[24:27], v[230:233], v[190:193], v[24:27]
	ds_read_b128 v[182:185], v174
	ds_read_b128 v[186:189], v175
	ds_read_b128 v[190:193], v176
	v_mfma_f32_16x16x32_bf16 v[20:23], v[222:225], v[198:201], v[20:23]
	v_mfma_f32_16x16x32_bf16 v[16:19], v[230:233], v[198:201], v[16:19]
	v_mfma_f32_16x16x32_bf16 v[12:15], v[222:225], v[206:209], v[12:15]
	v_mfma_f32_16x16x32_bf16 v[8:11], v[230:233], v[206:209], v[8:11]
	v_mfma_f32_16x16x32_bf16 v[4:7], v[222:225], v[214:217], v[4:7]
	v_mfma_f32_16x16x32_bf16 v[0:3], v[230:233], v[214:217], v[0:3]
	v_mfma_f32_16x16x32_bf16 v[28:31], v[226:229], v[194:197], v[28:31]
	v_mfma_f32_16x16x32_bf16 v[24:27], v[234:237], v[194:197], v[24:27]
	ds_read_b128 v[194:197], v177
	v_mfma_f32_16x16x32_bf16 v[20:23], v[226:229], v[202:205], v[20:23]
	v_mfma_f32_16x16x32_bf16 v[16:19], v[234:237], v[202:205], v[16:19]
	v_mfma_f32_16x16x32_bf16 v[12:15], v[226:229], v[210:213], v[12:15]
	v_mfma_f32_16x16x32_bf16 v[8:11], v[234:237], v[210:213], v[8:11]
	v_mfma_f32_16x16x32_bf16 v[4:7], v[226:229], v[218:221], v[4:7]
	v_mfma_f32_16x16x32_bf16 v[0:3], v[234:237], v[218:221], v[0:3]
	s_barrier
	v_mov_b32_e32 v178, v131
	v_mov_b32_e32 v128, v130
	ds_read_b128 v[198:201], v132 offset:32768
	ds_read_b128 v[202:205], v133 offset:32768
	ds_read_b128 v[206:209], v134 offset:32768
	ds_read_b128 v[210:213], v135 offset:32768
	ds_read_b128 v[214:217], v136 offset:32768
	ds_read_b128 v[218:221], v137 offset:32768
	ds_read_b128 v[222:225], v138 offset:32768
	ds_read_b128 v[226:229], v139 offset:32768
	v_readfirstlane_b32 s87, v148
	v_lshl_add_u64 v[180:181], s[44:45], 0, v[128:129]
	v_mov_b32_e32 v179, v129
	v_lshl_add_u64 v[180:181], v[180:181], 0, s[34:35]
	s_mov_b32 m0, s87
	v_lshl_add_u64 v[178:179], s[44:45], 0, v[178:179]
	v_readfirstlane_b32 s87, v149
	global_load_lds_dwordx4 v[180:181], off
	v_lshl_add_u64 v[178:179], v[178:179], 0, s[34:35]
	s_mov_b32 m0, s87
	s_nop 0
	global_load_lds_dwordx4 v[178:179], off
	s_waitcnt lgkmcnt(8)
	s_barrier
	s_waitcnt lgkmcnt(0)
	v_mfma_f32_16x16x32_bf16 v[124:127], v[182:185], v[198:201], v[124:127]
	v_mfma_f32_16x16x32_bf16 v[120:123], v[190:193], v[198:201], v[120:123]
	v_mfma_f32_16x16x32_bf16 v[116:119], v[182:185], v[206:209], v[116:119]
	v_mfma_f32_16x16x32_bf16 v[112:115], v[190:193], v[206:209], v[112:115]
	v_mfma_f32_16x16x32_bf16 v[108:111], v[182:185], v[214:217], v[108:111]
	v_mfma_f32_16x16x32_bf16 v[104:107], v[190:193], v[214:217], v[104:107]
	v_mfma_f32_16x16x32_bf16 v[100:103], v[182:185], v[222:225], v[100:103]
	v_mfma_f32_16x16x32_bf16 v[96:99], v[190:193], v[222:225], v[96:99]
	v_mfma_f32_16x16x32_bf16 v[124:127], v[186:189], v[202:205], v[124:127]
	v_mfma_f32_16x16x32_bf16 v[120:123], v[194:197], v[202:205], v[120:123]
	v_mfma_f32_16x16x32_bf16 v[116:119], v[186:189], v[210:213], v[116:119]
	v_mfma_f32_16x16x32_bf16 v[112:115], v[194:197], v[210:213], v[112:115]
	v_mfma_f32_16x16x32_bf16 v[108:111], v[186:189], v[218:221], v[108:111]
	v_mfma_f32_16x16x32_bf16 v[104:107], v[194:197], v[218:221], v[104:107]
	v_mfma_f32_16x16x32_bf16 v[100:103], v[186:189], v[226:229], v[100:103]
	v_mfma_f32_16x16x32_bf16 v[96:99], v[194:197], v[226:229], v[96:99]
	s_barrier
	v_add_u32_e32 v178, v159, v160
	v_add_u32_e32 v180, v159, v162
	v_mov_b32_e32 v246, v131
	v_mov_b32_e32 v128, v130
	v_add_u32_e32 v179, v159, v161
	ds_read_b128 v[230:233], v178
	ds_read_b128 v[234:237], v179
	v_add_u32_e32 v181, v159, v163
	ds_read_b128 v[238:241], v180
	ds_read_b128 v[242:245], v181
	v_readfirstlane_b32 s87, v150
	v_lshl_add_u64 v[248:249], s[52:53], 0, v[128:129]
	v_mov_b32_e32 v247, v129
	v_lshl_add_u64 v[248:249], v[248:249], 0, s[36:37]
	s_mov_b32 m0, s87
	v_lshl_add_u64 v[246:247], s[52:53], 0, v[246:247]
	v_readfirstlane_b32 s87, v151
	global_load_lds_dwordx4 v[248:249], off
	v_lshl_add_u64 v[246:247], v[246:247], 0, s[36:37]
	s_mov_b32 m0, s87
	s_nop 0
	global_load_lds_dwordx4 v[246:247], off
	s_barrier
	s_waitcnt lgkmcnt(0)
	v_mfma_f32_16x16x32_bf16 v[92:95], v[230:233], v[198:201], v[92:95]
	v_mfma_f32_16x16x32_bf16 v[88:91], v[238:241], v[198:201], v[88:91]
	v_mfma_f32_16x16x32_bf16 v[84:87], v[230:233], v[206:209], v[84:87]
	v_mfma_f32_16x16x32_bf16 v[80:83], v[238:241], v[206:209], v[80:83]
	v_mfma_f32_16x16x32_bf16 v[76:79], v[230:233], v[214:217], v[76:79]
	v_mfma_f32_16x16x32_bf16 v[72:75], v[238:241], v[214:217], v[72:75]
	v_mfma_f32_16x16x32_bf16 v[68:71], v[230:233], v[222:225], v[68:71]
	v_mfma_f32_16x16x32_bf16 v[64:67], v[238:241], v[222:225], v[64:67]
	v_mfma_f32_16x16x32_bf16 v[92:95], v[234:237], v[202:205], v[92:95]
	v_mfma_f32_16x16x32_bf16 v[88:91], v[242:245], v[202:205], v[88:91]
	v_mfma_f32_16x16x32_bf16 v[84:87], v[234:237], v[210:213], v[84:87]
	v_mfma_f32_16x16x32_bf16 v[80:83], v[242:245], v[210:213], v[80:83]
	v_mfma_f32_16x16x32_bf16 v[76:79], v[234:237], v[218:221], v[76:79]
	v_mfma_f32_16x16x32_bf16 v[72:75], v[242:245], v[218:221], v[72:75]
	v_mfma_f32_16x16x32_bf16 v[68:71], v[234:237], v[226:229], v[68:71]
	v_mfma_f32_16x16x32_bf16 v[64:67], v[242:245], v[226:229], v[64:67]
	v_mov_b32_e32 v246, v131
	v_mov_b32_e32 v128, v130
	s_barrier
; #define LDA(dst, b, h) for (int m = 0; m < 4; ++m) for (int k = 0; k < 2; ++k) \
;     dst[m][k] = *reinterpret_cast<const bf16x8*>((char*)SA(b, h) + lds_byte(wr * 64 + m * 16 + fr, k * 32 + fq * 8))
; #define LDB(dst, b, h) for (int n = 0; n < 2; ++n) for (int k = 0; k < 2; ++k) \
;     dst[n][k] = *reinterpret_cast<const bf16x8*>((char*)SB(b, h) + lds_byte(wc * 32 + n * 16 + fr, k * 32 + fq * 8))
; #define MMA(ai, bj, At_, Bt_) do { __builtin_amdgcn_s_setprio(1); \
;     for (int m = 0; m < 4; ++m) for (int n = 0; n < 2; ++n) for (int k = 0; k < 2; ++k) \
;       acc[ai][bj][m][n] = MFMA16(Bt_[n][k], At_[m][k], acc[ai][bj][m][n]); \
;     __builtin_amdgcn_s_setprio(0); } while (0)
; #define WAIT_V(n) asm volatile("s_waitcnt vmcnt(" #n ")" ::: "memory")
; #define WAIT_L(n) asm volatile("s_waitcnt lgkmcnt(" #n ")" ::: "memory")
; #define BAR __builtin_amdgcn_s_barrier()
; template <int PART  , bool SYNC_FIRST = true>
; __device__ __forceinline__ void kloop_t(const u16* __restrict__ A, int lda, const u16* __restrict__ Bt, int ldb, int K, Acc& acc, const int wv) {
;     ...
;     STAGE(SB(1, 1), Bt, ldb, HALF, t + 3);
;     WAIT_V(6); BAR; MMA(1, 1, At, B1); BAR;
;   }
;   { LDB(B0, 0, 0); LDA(At, 0, 0); STAGE(SA(1, 1), A, lda, HALF, nt - 1);
;     BAR; WAIT_L(0); MMA(0, 0, At, B0); BAR;
	ds_read_b128 v[198:201], v132 offset:49152
	ds_read_b128 v[202:205], v133 offset:49152
	ds_read_b128 v[206:209], v134 offset:49152
	ds_read_b128 v[210:213], v135 offset:49152
	ds_read_b128 v[214:217], v136 offset:49152
	ds_read_b128 v[218:221], v137 offset:49152
	ds_read_b128 v[222:225], v138 offset:49152
	ds_read_b128 v[226:229], v139 offset:49152
	v_readfirstlane_b32 s87, v152
	v_lshl_add_u64 v[248:249], s[44:45], 0, v[128:129]
	v_mov_b32_e32 v247, v129
	v_lshl_add_u64 v[248:249], v[248:249], 0, s[38:39]
	s_mov_b32 m0, s87
	v_lshl_add_u64 v[246:247], s[44:45], 0, v[246:247]
	v_readfirstlane_b32 s44, v153
	global_load_lds_dwordx4 v[248:249], off
	v_lshl_add_u64 v[246:247], v[246:247], 0, s[38:39]
	s_mov_b32 m0, s44
	s_nop 0
	global_load_lds_dwordx4 v[246:247], off
	s_waitcnt vmcnt(10)
	s_barrier
	s_waitcnt lgkmcnt(0)
	v_mfma_f32_16x16x32_bf16 v[60:63], v[182:185], v[198:201], v[60:63]
	v_mfma_f32_16x16x32_bf16 v[56:59], v[190:193], v[198:201], v[56:59]
	v_mfma_f32_16x16x32_bf16 v[52:55], v[182:185], v[206:209], v[52:55]
	v_mfma_f32_16x16x32_bf16 v[48:51], v[190:193], v[206:209], v[48:51]
	v_mfma_f32_16x16x32_bf16 v[44:47], v[182:185], v[214:217], v[44:47]
	v_mfma_f32_16x16x32_bf16 v[40:43], v[190:193], v[214:217], v[40:43]
	v_mfma_f32_16x16x32_bf16 v[36:39], v[182:185], v[222:225], v[36:39]
	v_mfma_f32_16x16x32_bf16 v[32:35], v[190:193], v[222:225], v[32:35]
	v_mfma_f32_16x16x32_bf16 v[60:63], v[186:189], v[202:205], v[60:63]
	v_mfma_f32_16x16x32_bf16 v[56:59], v[194:197], v[202:205], v[56:59]
	v_mfma_f32_16x16x32_bf16 v[52:55], v[186:189], v[210:213], v[52:55]
	v_mfma_f32_16x16x32_bf16 v[48:51], v[194:197], v[210:213], v[48:51]
	v_mfma_f32_16x16x32_bf16 v[44:47], v[186:189], v[218:221], v[44:47]
	v_mfma_f32_16x16x32_bf16 v[40:43], v[194:197], v[218:221], v[40:43]
	v_mfma_f32_16x16x32_bf16 v[36:39], v[186:189], v[226:229], v[36:39]
	v_mfma_f32_16x16x32_bf16 v[32:35], v[194:197], v[226:229], v[32:35]
	s_barrier
	v_mov_b32_e32 v182, v131
	v_mov_b32_e32 v128, v130
	v_readfirstlane_b32 s44, v154
	v_lshl_add_u64 v[184:185], s[52:53], 0, v[128:129]
	v_mov_b32_e32 v183, v129
	v_lshl_add_u64 v[184:185], v[184:185], 0, s[40:41]
	s_mov_b32 m0, s44
	v_lshl_add_u64 v[182:183], s[52:53], 0, v[182:183]
	v_readfirstlane_b32 s44, v155
	global_load_lds_dwordx4 v[184:185], off
	v_lshl_add_u64 v[182:183], v[182:183], 0, s[40:41]
	s_mov_b32 m0, s44
	s_nop 0
	global_load_lds_dwordx4 v[182:183], off
	s_waitcnt vmcnt(6)
	s_barrier
	v_mfma_f32_16x16x32_bf16 v[28:31], v[230:233], v[198:201], v[28:31]
	v_mfma_f32_16x16x32_bf16 v[24:27], v[238:241], v[198:201], v[24:27]
	ds_read_b128 v[174:177], v164
	ds_read_b128 v[178:181], v165
	ds_read_b128 v[182:185], v166
	ds_read_b128 v[186:189], v167
	v_mfma_f32_16x16x32_bf16 v[20:23], v[230:233], v[206:209], v[20:23]
	v_mfma_f32_16x16x32_bf16 v[16:19], v[238:241], v[206:209], v[16:19]
	v_mfma_f32_16x16x32_bf16 v[12:15], v[230:233], v[214:217], v[12:15]
	v_mfma_f32_16x16x32_bf16 v[8:11], v[238:241], v[214:217], v[8:11]
	v_mfma_f32_16x16x32_bf16 v[4:7], v[230:233], v[222:225], v[4:7]
	v_mfma_f32_16x16x32_bf16 v[0:3], v[238:241], v[222:225], v[0:3]
	v_mfma_f32_16x16x32_bf16 v[28:31], v[234:237], v[202:205], v[28:31]
	v_mfma_f32_16x16x32_bf16 v[24:27], v[242:245], v[202:205], v[24:27]
	v_mfma_f32_16x16x32_bf16 v[20:23], v[234:237], v[210:213], v[20:23]
	v_mfma_f32_16x16x32_bf16 v[16:19], v[242:245], v[210:213], v[16:19]
	v_mfma_f32_16x16x32_bf16 v[12:15], v[234:237], v[218:221], v[12:15]
	v_mfma_f32_16x16x32_bf16 v[8:11], v[242:245], v[218:221], v[8:11]
	v_mfma_f32_16x16x32_bf16 v[4:7], v[234:237], v[226:229], v[4:7]
	v_mfma_f32_16x16x32_bf16 v[0:3], v[242:245], v[226:229], v[0:3]
	s_add_i32 s57, s57, 2
	s_add_u32 s42, s42, 0x100
	s_addc_u32 s43, s43, 0
	s_cmp_lt_u32 s57, 60
	s_barrier
	s_cbranch_scc1 .LBB0_1139
	s_waitcnt lgkmcnt(0)
	v_add_u32_e32 v174, v158, v160
	v_add_u32_e32 v175, v158, v161
	v_add_u32_e32 v176, v158, v162
	v_add_u32_e32 v177, v158, v163
	v_add_u32_e32 v178, v159, v160
	v_add_u32_e32 v179, v159, v161
	v_add_u32_e32 v180, v159, v162
	v_add_u32_e32 v181, v159, v163
	s_add_u32 s4, s4, 0x101f80
	v_readfirstlane_b32 s42, v168
	s_addc_u32 s5, s5, 0
	s_mov_b32 m0, s42
	v_readfirstlane_b32 s42, v169
	ds_read_b128 v[142:145], v164
	ds_read_b128 v[146:149], v165
	ds_read_b128 v[150:153], v166
	ds_read_b128 v[154:157], v167
	ds_read_b128 v[158:161], v132
	ds_read_b128 v[162:165], v133
	ds_read_b128 v[182:185], v134
	ds_read_b128 v[186:189], v135
	ds_read_b128 v[190:193], v136
	ds_read_b128 v[194:197], v137
	ds_read_b128 v[198:201], v138
	ds_read_b128 v[202:205], v139
	s_nop 0
	global_load_lds_dwordx4 v130, s[4:5]
	s_mov_b32 m0, s42
	s_nop 0
	global_load_lds_dwordx4 v131, s[4:5]
	s_barrier
	s_waitcnt lgkmcnt(0)
	v_mfma_f32_16x16x32_bf16 v[124:127], v[142:145], v[158:161], v[124:127]
	v_mfma_f32_16x16x32_bf16 v[120:123], v[150:153], v[158:161], v[120:123]
	v_mfma_f32_16x16x32_bf16 v[108:111], v[142:145], v[190:193], v[108:111]
	v_mfma_f32_16x16x32_bf16 v[104:107], v[150:153], v[190:193], v[104:107]
	v_mfma_f32_16x16x32_bf16 v[124:127], v[146:149], v[162:165], v[124:127]
	v_mfma_f32_16x16x32_bf16 v[120:123], v[154:157], v[162:165], v[120:123]
	v_mfma_f32_16x16x32_bf16 v[116:119], v[142:145], v[182:185], v[116:119]
	v_mfma_f32_16x16x32_bf16 v[112:115], v[150:153], v[182:185], v[112:115]
	v_mfma_f32_16x16x32_bf16 v[108:111], v[146:149], v[194:197], v[108:111]
	v_mfma_f32_16x16x32_bf16 v[104:107], v[154:157], v[194:197], v[104:107]
	v_mfma_f32_16x16x32_bf16 v[100:103], v[142:145], v[198:201], v[100:103]
	v_mfma_f32_16x16x32_bf16 v[96:99], v[150:153], v[198:201], v[96:99]
	v_mfma_f32_16x16x32_bf16 v[166:169], v[146:149], v[186:189], v[116:119]
	v_mfma_f32_16x16x32_bf16 v[206:209], v[154:157], v[186:189], v[112:115]
	v_mfma_f32_16x16x32_bf16 v[210:213], v[146:149], v[202:205], v[100:103]
	v_mfma_f32_16x16x32_bf16 v[214:217], v[154:157], v[202:205], v[96:99]
	s_barrier
; #define LDA(dst, b, h) for (int m = 0; m < 4; ++m) for (int k = 0; k < 2; ++k) \
;     dst[m][k] = *reinterpret_cast<const bf16x8*>((char*)SA(b, h) + lds_byte(wr * 64 + m * 16 + fr, k * 32 + fq * 8))
; #define LDB(dst, b, h) for (int n = 0; n < 2; ++n) for (int k = 0; k < 2; ++k) \
;     dst[n][k] = *reinterpret_cast<const bf16x8*>((char*)SB(b, h) + lds_byte(wc * 32 + n * 16 + fr, k * 32 + fq * 8))
; #define MMA(ai, bj, At_, Bt_) do { __builtin_amdgcn_s_setprio(1); \
;     for (int m = 0; m < 4; ++m) for (int n = 0; n < 2; ++n) for (int k = 0; k < 2; ++k) \
;       acc[ai][bj][m][n] = MFMA16(Bt_[n][k], At_[m][k], acc[ai][bj][m][n]); \
;     __builtin_amdgcn_s_setprio(0); } while (0)
; #define WAIT_V(n) asm volatile("s_waitcnt vmcnt(" #n ")" ::: "memory")
; #define WAIT_L(n) asm volatile("s_waitcnt lgkmcnt(" #n ")" ::: "memory")
; #define BAR __builtin_amdgcn_s_barrier()
; template <int PART  , bool SYNC_FIRST = true>
; __device__ __forceinline__ void kloop_t(const u16* __restrict__ A, int lda, const u16* __restrict__ Bt, int ldb, int K, Acc& acc, const int wv) {
;     ...
;     LDB(B1, 0, 1); BAR; WAIT_L(0); MMA(0, 1, At, B1); BAR;
;     LDA(At, 0, 1); WAIT_V(4); BAR; WAIT_L(0); MMA(1, 0, At, B0); MMA(1, 1, At, B1); BAR; }
;   { LDB(B0, 1, 0); LDA(At, 1, 0); WAIT_V(2); BAR; WAIT_L(0); MMA(0, 0, At, B0); BAR;
	s_nop 1
	ds_read_b128 v[96:99], v170
	ds_read_b128 v[100:103], v171
	ds_read_b128 v[112:115], v172
	ds_read_b128 v[116:119], v173
	s_barrier
	s_waitcnt lgkmcnt(0)
	v_mfma_f32_16x16x32_bf16 v[92:95], v[96:99], v[158:161], v[92:95]
	v_mfma_f32_16x16x32_bf16 v[88:91], v[112:115], v[158:161], v[88:91]
	v_mfma_f32_16x16x32_bf16 v[76:79], v[96:99], v[190:193], v[76:79]
	v_mfma_f32_16x16x32_bf16 v[72:75], v[112:115], v[190:193], v[72:75]
	v_mfma_f32_16x16x32_bf16 v[92:95], v[100:103], v[162:165], v[92:95]
	v_mfma_f32_16x16x32_bf16 v[88:91], v[116:119], v[162:165], v[88:91]
	v_mfma_f32_16x16x32_bf16 v[84:87], v[96:99], v[182:185], v[84:87]
	v_mfma_f32_16x16x32_bf16 v[80:83], v[112:115], v[182:185], v[80:83]
	v_mfma_f32_16x16x32_bf16 v[76:79], v[100:103], v[194:197], v[76:79]
	v_mfma_f32_16x16x32_bf16 v[72:75], v[116:119], v[194:197], v[72:75]
	v_mfma_f32_16x16x32_bf16 v[68:71], v[96:99], v[198:201], v[68:71]
	v_mfma_f32_16x16x32_bf16 v[64:67], v[112:115], v[198:201], v[64:67]
	v_mfma_f32_16x16x32_bf16 v[158:161], v[100:103], v[186:189], v[84:87]
	v_mfma_f32_16x16x32_bf16 v[162:165], v[116:119], v[186:189], v[80:83]
	v_mfma_f32_16x16x32_bf16 v[170:173], v[100:103], v[202:205], v[68:71]
	v_mfma_f32_16x16x32_bf16 v[182:185], v[116:119], v[202:205], v[64:67]
	s_barrier
	s_nop 1
	ds_read_b128 v[64:67], v132 offset:16384
	ds_read_b128 v[68:71], v133 offset:16384
	ds_read_b128 v[80:83], v134 offset:16384
	ds_read_b128 v[84:87], v135 offset:16384
	ds_read_b128 v[186:189], v136 offset:16384
	ds_read_b128 v[190:193], v137 offset:16384
	ds_read_b128 v[194:197], v138 offset:16384
	ds_read_b128 v[198:201], v139 offset:16384
	s_waitcnt vmcnt(4)
	s_barrier
	s_waitcnt lgkmcnt(0)
	v_mfma_f32_16x16x32_bf16 v[60:63], v[142:145], v[64:67], v[60:63]
	v_mfma_f32_16x16x32_bf16 v[56:59], v[150:153], v[64:67], v[56:59]
	v_mfma_f32_16x16x32_bf16 v[44:47], v[142:145], v[186:189], v[44:47]
	v_mfma_f32_16x16x32_bf16 v[40:43], v[150:153], v[186:189], v[40:43]
	v_mfma_f32_16x16x32_bf16 v[60:63], v[146:149], v[68:71], v[60:63]
	v_mfma_f32_16x16x32_bf16 v[56:59], v[154:157], v[68:71], v[56:59]
	v_mfma_f32_16x16x32_bf16 v[52:55], v[142:145], v[80:83], v[52:55]
	v_mfma_f32_16x16x32_bf16 v[48:51], v[150:153], v[80:83], v[48:51]
	v_mfma_f32_16x16x32_bf16 v[44:47], v[146:149], v[190:193], v[44:47]
	v_mfma_f32_16x16x32_bf16 v[40:43], v[154:157], v[190:193], v[40:43]
	v_mfma_f32_16x16x32_bf16 v[36:39], v[142:145], v[194:197], v[36:39]
	v_mfma_f32_16x16x32_bf16 v[32:35], v[150:153], v[194:197], v[32:35]
	v_mfma_f32_16x16x32_bf16 v[202:205], v[146:149], v[84:87], v[52:55]
	v_mfma_f32_16x16x32_bf16 v[218:221], v[154:157], v[84:87], v[48:51]
	v_mfma_f32_16x16x32_bf16 v[142:145], v[146:149], v[198:201], v[36:39]
	v_mfma_f32_16x16x32_bf16 v[146:149], v[154:157], v[198:201], v[32:35]
	v_mfma_f32_16x16x32_bf16 v[28:31], v[96:99], v[64:67], v[28:31]
	v_mfma_f32_16x16x32_bf16 v[24:27], v[112:115], v[64:67], v[24:27]
	v_mfma_f32_16x16x32_bf16 v[12:15], v[96:99], v[186:189], v[12:15]
	v_mfma_f32_16x16x32_bf16 v[8:11], v[112:115], v[186:189], v[8:11]
	v_mfma_f32_16x16x32_bf16 v[28:31], v[100:103], v[68:71], v[28:31]
	v_mfma_f32_16x16x32_bf16 v[24:27], v[116:119], v[68:71], v[24:27]
	v_mfma_f32_16x16x32_bf16 v[20:23], v[96:99], v[80:83], v[20:23]
	v_mfma_f32_16x16x32_bf16 v[16:19], v[112:115], v[80:83], v[16:19]
	v_mfma_f32_16x16x32_bf16 v[12:15], v[100:103], v[190:193], v[12:15]
	v_mfma_f32_16x16x32_bf16 v[8:11], v[116:119], v[190:193], v[8:11]
	v_mfma_f32_16x16x32_bf16 v[4:7], v[96:99], v[194:197], v[4:7]
	v_mfma_f32_16x16x32_bf16 v[0:3], v[112:115], v[194:197], v[0:3]
	v_mfma_f32_16x16x32_bf16 v[150:153], v[100:103], v[84:87], v[20:23]
	v_mfma_f32_16x16x32_bf16 v[154:157], v[116:119], v[84:87], v[16:19]
	v_mfma_f32_16x16x32_bf16 v[186:189], v[100:103], v[198:201], v[4:7]
	v_mfma_f32_16x16x32_bf16 v[190:193], v[116:119], v[198:201], v[0:3]
	s_barrier
	s_nop 1
	ds_read_b128 v[0:3], v174
	ds_read_b128 v[4:7], v175
	ds_read_b128 v[194:197], v176
	ds_read_b128 v[174:177], v177
	ds_read_b128 v[16:19], v132 offset:32768
	ds_read_b128 v[20:23], v133 offset:32768
	ds_read_b128 v[32:35], v134 offset:32768
	ds_read_b128 v[36:39], v135 offset:32768
	ds_read_b128 v[48:51], v136 offset:32768
	ds_read_b128 v[52:55], v137 offset:32768
	ds_read_b128 v[198:201], v138 offset:32768
	ds_read_b128 v[222:225], v139 offset:32768
	s_waitcnt vmcnt(2)
	s_barrier
; #define LDA(dst, b, h) for (int m = 0; m < 4; ++m) for (int k = 0; k < 2; ++k) \
;     dst[m][k] = *reinterpret_cast<const bf16x8*>((char*)SA(b, h) + lds_byte(wr * 64 + m * 16 + fr, k * 32 + fq * 8))
; #define LDB(dst, b, h) for (int n = 0; n < 2; ++n) for (int k = 0; k < 2; ++k) \
;     dst[n][k] = *reinterpret_cast<const bf16x8*>((char*)SB(b, h) + lds_byte(wc * 32 + n * 16 + fr, k * 32 + fq * 8))
; #define MMA(ai, bj, At_, Bt_) do { __builtin_amdgcn_s_setprio(1); \
;     for (int m = 0; m < 4; ++m) for (int n = 0; n < 2; ++n) for (int k = 0; k < 2; ++k) \
;       acc[ai][bj][m][n] = MFMA16(Bt_[n][k], At_[m][k], acc[ai][bj][m][n]); \
;     __builtin_amdgcn_s_setprio(0); } while (0)
; #define WAIT_V(n) asm volatile("s_waitcnt vmcnt(" #n ")" ::: "memory")
; #define WAIT_L(n) asm volatile("s_waitcnt lgkmcnt(" #n ")" ::: "memory")
; #define BAR __builtin_amdgcn_s_barrier()
; template <int PART  , bool SYNC_FIRST = true>
; __device__ __forceinline__ void kloop_t(const u16* __restrict__ A, int lda, const u16* __restrict__ Bt, int ldb, int K, Acc& acc, const int wv) {
;     ...
;   { LDB(B0, 1, 0); LDA(At, 1, 0); WAIT_V(2); BAR; WAIT_L(0); MMA(0, 0, At, B0); BAR;
;     LDB(B1, 1, 1); WAIT_V(0); BAR; WAIT_L(0); MMA(0, 1, At, B1); BAR;
;     LDA(At, 1, 1); BAR; WAIT_L(0); MMA(1, 0, At, B0); MMA(1, 1, At, B1); BAR; }
;   if (wr == 0) BAR;
	s_waitcnt lgkmcnt(0)
	v_mfma_f32_16x16x32_bf16 v[64:67], v[0:3], v[16:19], v[124:127]
	v_mfma_f32_16x16x32_bf16 v[112:115], v[4:7], v[20:23], v[64:67]
	v_mfma_f32_16x16x32_bf16 v[64:67], v[194:197], v[16:19], v[120:123]
	v_mfma_f32_16x16x32_bf16 v[116:119], v[174:177], v[20:23], v[64:67]
	v_mfma_f32_16x16x32_bf16 v[64:67], v[0:3], v[32:35], v[166:169]
	v_mfma_f32_16x16x32_bf16 v[96:99], v[4:7], v[36:39], v[64:67]
	v_mfma_f32_16x16x32_bf16 v[64:67], v[194:197], v[32:35], v[206:209]
	v_mfma_f32_16x16x32_bf16 v[100:103], v[174:177], v[36:39], v[64:67]
	v_mfma_f32_16x16x32_bf16 v[64:67], v[0:3], v[48:51], v[108:111]
	v_mfma_f32_16x16x32_bf16 v[80:83], v[4:7], v[52:55], v[64:67]
	v_mfma_f32_16x16x32_bf16 v[64:67], v[194:197], v[48:51], v[104:107]
	v_mfma_f32_16x16x32_bf16 v[84:87], v[174:177], v[52:55], v[64:67]
	v_mfma_f32_16x16x32_bf16 v[64:67], v[0:3], v[198:201], v[210:213]
	v_mfma_f32_16x16x32_bf16 v[68:71], v[194:197], v[198:201], v[214:217]
	v_mfma_f32_16x16x32_bf16 v[64:67], v[4:7], v[222:225], v[64:67]
	v_mfma_f32_16x16x32_bf16 v[68:71], v[174:177], v[222:225], v[68:71]
	s_barrier
	ds_read_b128 v[166:169], v178
	ds_read_b128 v[206:209], v179
	ds_read_b128 v[210:213], v180
	ds_read_b128 v[178:181], v181
	s_waitcnt vmcnt(0)
	s_barrier
	s_waitcnt lgkmcnt(0)
	v_mfma_f32_16x16x32_bf16 v[92:95], v[166:169], v[16:19], v[92:95]
	v_mfma_f32_16x16x32_bf16 v[16:19], v[210:213], v[16:19], v[88:91]
	v_mfma_f32_16x16x32_bf16 v[124:127], v[178:181], v[20:23], v[16:19]
	v_mfma_f32_16x16x32_bf16 v[16:19], v[166:169], v[32:35], v[158:161]
	v_mfma_f32_16x16x32_bf16 v[104:107], v[206:209], v[36:39], v[16:19]
	v_mfma_f32_16x16x32_bf16 v[16:19], v[210:213], v[32:35], v[162:165]
	v_mfma_f32_16x16x32_bf16 v[108:111], v[178:181], v[36:39], v[16:19]
	v_mfma_f32_16x16x32_bf16 v[16:19], v[166:169], v[48:51], v[76:79]
	v_mfma_f32_16x16x32_bf16 v[88:91], v[206:209], v[52:55], v[16:19]
	v_mfma_f32_16x16x32_bf16 v[16:19], v[210:213], v[48:51], v[72:75]
	v_mfma_f32_16x16x32_bf16 v[120:123], v[206:209], v[20:23], v[92:95]
	v_mfma_f32_16x16x32_bf16 v[92:95], v[178:181], v[52:55], v[16:19]
	v_mfma_f32_16x16x32_bf16 v[16:19], v[166:169], v[198:201], v[170:173]
	v_mfma_f32_16x16x32_bf16 v[72:75], v[206:209], v[222:225], v[16:19]
	v_mfma_f32_16x16x32_bf16 v[16:19], v[210:213], v[198:201], v[182:185]
	v_mfma_f32_16x16x32_bf16 v[76:79], v[178:181], v[222:225], v[16:19]
	s_barrier
	ds_read_b128 v[158:161], v132 offset:49152
	ds_read_b128 v[130:133], v133 offset:49152
	ds_read_b128 v[162:165], v134 offset:49152
	ds_read_b128 v[170:173], v135 offset:49152
	ds_read_b128 v[182:185], v136 offset:49152
	ds_read_b128 v[134:137], v137 offset:49152
	ds_read_b128 v[198:201], v138 offset:49152
	ds_read_b128 v[214:217], v139 offset:49152
	s_barrier
	s_waitcnt lgkmcnt(0)
	v_mfma_f32_16x16x32_bf16 v[16:19], v[0:3], v[158:161], v[60:63]
	v_mfma_f32_16x16x32_bf16 v[48:51], v[4:7], v[130:133], v[16:19]
	v_mfma_f32_16x16x32_bf16 v[16:19], v[194:197], v[158:161], v[56:59]
	v_mfma_f32_16x16x32_bf16 v[52:55], v[174:177], v[130:133], v[16:19]
	v_mfma_f32_16x16x32_bf16 v[16:19], v[0:3], v[162:165], v[202:205]
	v_mfma_f32_16x16x32_bf16 v[32:35], v[4:7], v[170:173], v[16:19]
	v_mfma_f32_16x16x32_bf16 v[16:19], v[194:197], v[162:165], v[218:221]
	v_mfma_f32_16x16x32_bf16 v[36:39], v[174:177], v[170:173], v[16:19]
	v_mfma_f32_16x16x32_bf16 v[16:19], v[0:3], v[182:185], v[44:47]
	v_mfma_f32_16x16x32_bf16 v[0:3], v[0:3], v[198:201], v[142:145]
	v_mfma_f32_16x16x32_bf16 v[16:19], v[4:7], v[134:137], v[16:19]
	v_mfma_f32_16x16x32_bf16 v[20:23], v[194:197], v[182:185], v[40:43]
	v_mfma_f32_16x16x32_bf16 v[0:3], v[4:7], v[214:217], v[0:3]
	v_mfma_f32_16x16x32_bf16 v[4:7], v[194:197], v[198:201], v[146:149]
	v_mfma_f32_16x16x32_bf16 v[20:23], v[174:177], v[134:137], v[20:23]
	v_mfma_f32_16x16x32_bf16 v[4:7], v[174:177], v[214:217], v[4:7]
	v_mfma_f32_16x16x32_bf16 v[24:27], v[210:213], v[158:161], v[24:27]
	v_mfma_f32_16x16x32_bf16 v[60:63], v[178:181], v[130:133], v[24:27]
	v_mfma_f32_16x16x32_bf16 v[24:27], v[166:169], v[162:165], v[150:153]
	v_mfma_f32_16x16x32_bf16 v[28:31], v[166:169], v[158:161], v[28:31]
	v_mfma_f32_16x16x32_bf16 v[40:43], v[206:209], v[170:173], v[24:27]
	v_mfma_f32_16x16x32_bf16 v[24:27], v[210:213], v[162:165], v[154:157]
	v_mfma_f32_16x16x32_bf16 v[12:15], v[166:169], v[182:185], v[12:15]
	v_mfma_f32_16x16x32_bf16 v[8:11], v[210:213], v[182:185], v[8:11]
	v_mfma_f32_16x16x32_bf16 v[56:59], v[206:209], v[130:133], v[28:31]
	v_mfma_f32_16x16x32_bf16 v[44:47], v[178:181], v[170:173], v[24:27]
	v_mfma_f32_16x16x32_bf16 v[24:27], v[206:209], v[134:137], v[12:15]
	v_mfma_f32_16x16x32_bf16 v[28:31], v[178:181], v[134:137], v[8:11]
	v_mfma_f32_16x16x32_bf16 v[8:11], v[166:169], v[198:201], v[186:189]
	v_mfma_f32_16x16x32_bf16 v[12:15], v[210:213], v[198:201], v[190:193]
	v_mfma_f32_16x16x32_bf16 v[8:11], v[206:209], v[214:217], v[8:11]
	v_mfma_f32_16x16x32_bf16 v[12:15], v[178:181], v[214:217], v[12:15]
	s_andn2_b64 vcc, exec, s[16:17]
	s_barrier
	s_cbranch_vccnz .LBB0_1142
	s_barrier
